# P5: residual tile (h1) touched three K iterations before the end (L2 warm-up for the epilogue's load burst)
# baseline (speedup 1.0000x reference)
;     __device__ __forceinline__ void operator()(const f32x4 (&acc)[2][2][4][2], const Unit& u, int wr, int wc, int fr_, int fq_) const {
;     ...
;         f16x8 hb[2][4][2]; float bsc[2][4];
; #pragma unroll
;         for (int ai = 0; ai < 2; ++ai)
; #pragma unroll
;             for (int m = 0; m < 4; ++m) { const size_t off = (size_t)(r0 + ai * HALF + m * 16) * D + col0;
;                 bsc[ai][m] = SCALED ? bscale[r0 + ai * HALF + m * 16] : 1.0f;
; #pragma unroll
;                 for (int bj = 0; bj < 2; ++bj) hb[ai][m][bj] = *(const f16x8*)(base + off + bj * HALF); }
;     ...
;         for (int t = 0; t < nt; t += 2) {
;             const bool last = (t == nt - 2);
;             const char* a1 = cA + (size_t)(t + 1) * kstep;
;             const char* a2 = last ? nA : cA + (size_t)(t + 2) * kstep; const char* b2 = last ? nB : cB + (size_t)(t + 2) * kstep;
;             const char* a3 = a2 + kstep; const char* b3 = b2 + kstep;
;             if (last && has_next) S.a_ready(nxt);
.LBB0_989:
	s_cmp_eq_u32 s54, 38
	s_cbranch_scc0 .Lwarm_p5_skip
	s_lshl_b32 s98, s61, 19
	s_lshl_b32 s99, s62, 9
	s_add_i32 s98, s98, s99
	v_lshrrev_b32_e32 v252, 1, v0
	v_and_b32_e32 v253, 1, v0
	v_lshlrev_b32_e32 v253, 8, v253
	v_lshl_add_u32 v252, v252, 11, v253
	v_add_u32_e32 v252, s98, v252
	global_load_dword v253, v252, s[74:75]
	global_load_dword v253, v252, s[74:75] offset:128
